# P8 K-loop stage loads in SGPR-base form (no VALU address adds) on top of one-barrier version
# speedup vs baseline: 1.3375x; 1.0009x over previous
; #define PG8_STAGE(bufoff, gbase, voff) do { _Pragma("unroll") for (int _i = 0; _i < 2; ++_i) \
;         __builtin_amdgcn_global_load_lds((const unsigned*)((const char*)(gbase) + (voff)[_i]), (PG8_LAS unsigned*)(lds + (bufoff) + ldsw + _i * 8192), 16, 0, 0); } while (0)
; #define PG8_LDA(dst, b, h) do { _Pragma("unroll") for (int m = 0; m < 4; ++m) _Pragma("unroll") for (int k = 0; k < 2; ++k) dst[m][k] = *(const PG8_LAS bf16x8*)(lds + PG8_SA(b, h) + aoff + m * 2048 + k * 1024); } while (0)
; #define PG8_LDB(dst, b, h) do { _Pragma("unroll") for (int n = 0; n < 2; ++n) _Pragma("unroll") for (int k = 0; k < 2; ++k) dst[n][k] = *(const PG8_LAS bf16x8*)(lds + PG8_SB(b, h) + boff + n * 2048 + k * 1024); } while (0)
; #define PG8_WAIT_V(n) asm volatile("s_waitcnt vmcnt(" #n ")" ::: "memory")
; #define PG8_WAIT_L(n) asm volatile("s_waitcnt lgkmcnt(" #n ")" ::: "memory")
; #define PG8_BAR __builtin_amdgcn_s_barrier()
; #define PG8_SCHED __builtin_amdgcn_sched_barrier(0)
; template <class Epi, class Sched, bool ALIGN_EPI = false, bool SP2 = false, bool F8 = false>
; __device__ __forceinline__ void gemm_phase(PG8_LAS unsigned char* lds, const Gemm g, const Sched& S, const Epi& E) {
;     ...
;             PG8_LDB(B0, 0, 0); PG8_LDB(B1, 0, 1); PG8_SCHED; PG8_LDA(At, 0, 0); PG8_STAGE(PG8_SA(1, 1), a1 + hstepA, voffA);
;             PG8_WAIT_V(8); PG8_WAIT_L(0); PG8_BAR; PG8_MMA(0, 0, At, B0); PG8_MMA(0, 1, At, B1); PG8_BAR; PG8_SCHED;
;             PG8_LDA(At, 0, 1); PG8_STAGE(PG8_SB(0, 0), b2, voffB); PG8_STAGE(PG8_SB(0, 1), b2 + hstep, voffB); PG8_STAGE(PG8_SA(0, 0), a2, voffA);
;             PG8_WAIT_V(8); PG8_WAIT_L(0); PG8_BAR; PG8_MMA(1, 0, At, B0); PG8_MMA(1, 1, At, B1); PG8_BAR; PG8_SCHED;
.LBB0_917:
	ds_read_b128 v[146:149], v175
	ds_read_b128 v[150:153], v175 offset:1024
	ds_read_b128 v[154:157], v175 offset:2048
	ds_read_b128 v[158:161], v175 offset:3072
	ds_read_b128 v[162:165], v176
	ds_read_b128 v[166:169], v176 offset:1024
	ds_read_b128 v[186:189], v176 offset:2048
	ds_read_b128 v[190:193], v176 offset:3072
	s_add_u32 s6, s56, 0x100
	s_addc_u32 s7, s57, 0
	s_cmp_eq_u32 s29, 28
	s_cselect_b32 s61, s53, s7
	s_cselect_b32 s60, s52, s6
	s_cselect_b32 s59, s15, s28
	s_cselect_b32 s58, s26, s27
	ds_read_b128 v[194:197], v177
	ds_read_b128 v[198:201], v177 offset:1024
	ds_read_b128 v[202:205], v177 offset:2048
	ds_read_b128 v[206:209], v177 offset:3072
	ds_read_b128 v[210:213], v177 offset:4096
	ds_read_b128 v[218:221], v177 offset:5120
	ds_read_b128 v[222:225], v177 offset:6144
	ds_read_b128 v[226:229], v177 offset:7168
	s_add_i32 m0, s65, 0xc000
	s_nop 0
	global_load_lds_dwordx4 v138, s[56:57]
	s_add_i32 m0, s65, 0xe000
	s_nop 0
	global_load_lds_dwordx4 v140, s[56:57]
	s_waitcnt vmcnt(8)
	s_waitcnt lgkmcnt(0)
	s_setprio 1
	s_waitcnt lgkmcnt(0)
	v_mfma_f32_16x16x32_bf16 v[126:129], v[146:149], v[194:197], v[126:129]
	v_mfma_f32_16x16x32_bf16 v[122:125], v[154:157], v[194:197], v[122:125]
	v_mfma_f32_16x16x32_bf16 v[118:121], v[146:149], v[202:205], v[118:121]
	v_mfma_f32_16x16x32_bf16 v[114:117], v[154:157], v[202:205], v[114:117]
	v_mfma_f32_16x16x32_bf16 v[110:113], v[146:149], v[210:213], v[110:113]
	v_mfma_f32_16x16x32_bf16 v[102:105], v[154:157], v[210:213], v[102:105]
	v_mfma_f32_16x16x32_bf16 v[94:97], v[146:149], v[222:225], v[94:97]
	v_mfma_f32_16x16x32_bf16 v[86:89], v[154:157], v[222:225], v[86:89]
	v_mfma_f32_16x16x32_bf16 v[126:129], v[150:153], v[198:201], v[126:129]
	v_mfma_f32_16x16x32_bf16 v[122:125], v[158:161], v[198:201], v[122:125]
	v_mfma_f32_16x16x32_bf16 v[118:121], v[150:153], v[206:209], v[118:121]
	v_mfma_f32_16x16x32_bf16 v[114:117], v[158:161], v[206:209], v[114:117]
	v_mfma_f32_16x16x32_bf16 v[110:113], v[150:153], v[218:221], v[110:113]
	v_mfma_f32_16x16x32_bf16 v[102:105], v[158:161], v[218:221], v[102:105]
	v_mfma_f32_16x16x32_bf16 v[94:97], v[150:153], v[226:229], v[94:97]
	v_mfma_f32_16x16x32_bf16 v[86:89], v[158:161], v[226:229], v[86:89]
	s_setprio 0
	s_setprio 1
	v_mfma_f32_16x16x32_bf16 v[106:109], v[162:165], v[194:197], v[106:109]
	v_mfma_f32_16x16x32_bf16 v[98:101], v[186:189], v[194:197], v[98:101]
	v_mfma_f32_16x16x32_bf16 v[90:93], v[162:165], v[202:205], v[90:93]
	v_mfma_f32_16x16x32_bf16 v[82:85], v[186:189], v[202:205], v[82:85]
	v_mfma_f32_16x16x32_bf16 v[78:81], v[162:165], v[210:213], v[78:81]
	v_mfma_f32_16x16x32_bf16 v[74:77], v[186:189], v[210:213], v[74:77]
	v_mfma_f32_16x16x32_bf16 v[70:73], v[162:165], v[222:225], v[70:73]
	v_mfma_f32_16x16x32_bf16 v[66:69], v[186:189], v[222:225], v[66:69]
	v_mfma_f32_16x16x32_bf16 v[106:109], v[166:169], v[198:201], v[106:109]
	v_mfma_f32_16x16x32_bf16 v[98:101], v[190:193], v[198:201], v[98:101]
	v_mfma_f32_16x16x32_bf16 v[90:93], v[166:169], v[206:209], v[90:93]
	v_mfma_f32_16x16x32_bf16 v[82:85], v[190:193], v[206:209], v[82:85]
	v_mfma_f32_16x16x32_bf16 v[78:81], v[166:169], v[218:221], v[78:81]
	v_mfma_f32_16x16x32_bf16 v[74:77], v[190:193], v[218:221], v[74:77]
	v_mfma_f32_16x16x32_bf16 v[70:73], v[166:169], v[226:229], v[70:73]
	v_mfma_f32_16x16x32_bf16 v[66:69], v[190:193], v[226:229], v[66:69]
	s_setprio 0
	s_barrier
	ds_read_b128 v[194:197], v177 offset:16384
	ds_read_b128 v[198:201], v177 offset:17408
	ds_read_b128 v[202:205], v177 offset:18432
	ds_read_b128 v[206:209], v177 offset:19456
	ds_read_b128 v[210:213], v177 offset:20480
	ds_read_b128 v[218:221], v177 offset:21504
	ds_read_b128 v[222:225], v177 offset:22528
	ds_read_b128 v[226:229], v177 offset:23552
	s_add_u32 s98, s58, 0x80000
	s_addc_u32 s99, s59, 0
	s_add_i32 s100, s75, s62
	s_add_i32 s101, s76, s62
	s_mov_b32 m0, s100
	s_nop 0
	global_load_lds_dwordx4 v134, s[58:59]
	s_add_i32 m0, s100, 0x2000
	s_nop 0
	global_load_lds_dwordx4 v130, s[58:59]
	s_mov_b32 m0, s101
	s_nop 0
	global_load_lds_dwordx4 v134, s[98:99]
	s_add_i32 m0, s101, 0x2000
	s_nop 0
	global_load_lds_dwordx4 v130, s[98:99]
	s_mov_b32 m0, s65
	s_nop 0
	global_load_lds_dwordx4 v136, s[60:61]
	s_mov_b32 m0, s66
	s_nop 0
	global_load_lds_dwordx4 v132, s[60:61]
	s_waitcnt vmcnt(8)
	s_waitcnt lgkmcnt(0)
	s_setprio 1
	s_waitcnt lgkmcnt(0)
	v_mfma_f32_16x16x32_bf16 v[62:65], v[146:149], v[194:197], v[62:65]
	v_mfma_f32_16x16x32_bf16 v[58:61], v[154:157], v[194:197], v[58:61]
	v_mfma_f32_16x16x32_bf16 v[54:57], v[146:149], v[202:205], v[54:57]
	v_mfma_f32_16x16x32_bf16 v[50:53], v[154:157], v[202:205], v[50:53]
	v_mfma_f32_16x16x32_bf16 v[38:41], v[146:149], v[210:213], v[38:41]
	v_mfma_f32_16x16x32_bf16 v[34:37], v[154:157], v[210:213], v[34:37]
	v_mfma_f32_16x16x32_bf16 v[22:25], v[146:149], v[222:225], v[22:25]
	v_mfma_f32_16x16x32_bf16 v[18:21], v[154:157], v[222:225], v[18:21]
	v_mfma_f32_16x16x32_bf16 v[62:65], v[150:153], v[198:201], v[62:65]
	v_mfma_f32_16x16x32_bf16 v[58:61], v[158:161], v[198:201], v[58:61]
	v_mfma_f32_16x16x32_bf16 v[54:57], v[150:153], v[206:209], v[54:57]
	v_mfma_f32_16x16x32_bf16 v[50:53], v[158:161], v[206:209], v[50:53]
	v_mfma_f32_16x16x32_bf16 v[38:41], v[150:153], v[218:221], v[38:41]
	v_mfma_f32_16x16x32_bf16 v[34:37], v[158:161], v[218:221], v[34:37]
	v_mfma_f32_16x16x32_bf16 v[22:25], v[150:153], v[226:229], v[22:25]
	v_mfma_f32_16x16x32_bf16 v[18:21], v[158:161], v[226:229], v[18:21]
	s_setprio 0
	s_setprio 1
	v_mfma_f32_16x16x32_bf16 v[46:49], v[162:165], v[194:197], v[46:49]
	v_mfma_f32_16x16x32_bf16 v[42:45], v[186:189], v[194:197], v[42:45]
	v_mfma_f32_16x16x32_bf16 v[30:33], v[162:165], v[202:205], v[30:33]
	v_mfma_f32_16x16x32_bf16 v[26:29], v[186:189], v[202:205], v[26:29]
	v_mfma_f32_16x16x32_bf16 v[14:17], v[162:165], v[210:213], v[14:17]
	v_mfma_f32_16x16x32_bf16 v[10:13], v[186:189], v[210:213], v[10:13]
	v_mfma_f32_16x16x32_bf16 v[6:9], v[162:165], v[222:225], v[6:9]
	v_mfma_f32_16x16x32_bf16 v[2:5], v[186:189], v[222:225], v[2:5]
	v_mfma_f32_16x16x32_bf16 v[46:49], v[166:169], v[198:201], v[46:49]
	v_mfma_f32_16x16x32_bf16 v[42:45], v[190:193], v[198:201], v[42:45]
	v_mfma_f32_16x16x32_bf16 v[30:33], v[166:169], v[206:209], v[30:33]
	v_mfma_f32_16x16x32_bf16 v[26:29], v[190:193], v[206:209], v[26:29]
	v_mfma_f32_16x16x32_bf16 v[14:17], v[166:169], v[218:221], v[14:17]
	v_mfma_f32_16x16x32_bf16 v[10:13], v[190:193], v[218:221], v[10:13]
	v_mfma_f32_16x16x32_bf16 v[6:9], v[166:169], v[226:229], v[6:9]
	v_mfma_f32_16x16x32_bf16 v[2:5], v[190:193], v[226:229], v[2:5]
	s_setprio 0
	s_barrier
; #define PG8_STAGE(bufoff, gbase, voff) do { _Pragma("unroll") for (int _i = 0; _i < 2; ++_i) \
;         __builtin_amdgcn_global_load_lds((const unsigned*)((const char*)(gbase) + (voff)[_i]), (PG8_LAS unsigned*)(lds + (bufoff) + ldsw + _i * 8192), 16, 0, 0); } while (0)
; #define PG8_LDA(dst, b, h) do { _Pragma("unroll") for (int m = 0; m < 4; ++m) _Pragma("unroll") for (int k = 0; k < 2; ++k) dst[m][k] = *(const PG8_LAS bf16x8*)(lds + PG8_SA(b, h) + aoff + m * 2048 + k * 1024); } while (0)
; #define PG8_LDB(dst, b, h) do { _Pragma("unroll") for (int n = 0; n < 2; ++n) _Pragma("unroll") for (int k = 0; k < 2; ++k) dst[n][k] = *(const PG8_LAS bf16x8*)(lds + PG8_SB(b, h) + boff + n * 2048 + k * 1024); } while (0)
; #define PG8_WAIT_V(n) asm volatile("s_waitcnt vmcnt(" #n ")" ::: "memory")
; #define PG8_WAIT_L(n) asm volatile("s_waitcnt lgkmcnt(" #n ")" ::: "memory")
; #define PG8_BAR __builtin_amdgcn_s_barrier()
; #define PG8_SCHED __builtin_amdgcn_sched_barrier(0)
; template <class Epi, class Sched, bool ALIGN_EPI = false, bool SP2 = false, bool F8 = false>
; __device__ __forceinline__ void gemm_phase(PG8_LAS unsigned char* lds, const Gemm g, const Sched& S, const Epi& E) {
;     ...
;             PG8_LDB(B0, 1, 0); PG8_LDB(B1, 1, 1); PG8_SCHED; PG8_LDA(At, 1, 0); PG8_STAGE(PG8_SA(0, 1), a2 + hstepA, voffA);
;             PG8_WAIT_V(8); PG8_WAIT_L(0); PG8_BAR; PG8_MMA(0, 0, At, B0); PG8_MMA(0, 1, At, B1); PG8_BAR; PG8_SCHED;
;             PG8_LDA(At, 1, 1); PG8_STAGE(PG8_SB(1, 0), b3, voffB); PG8_STAGE(PG8_SB(1, 1), b3 + hstep, voffB); PG8_STAGE(PG8_SA(1, 0), a3, voffA);
;             PG8_WAIT_V(8); PG8_WAIT_L(0); PG8_BAR; PG8_MMA(1, 0, At, B0); PG8_MMA(1, 1, At, B1); PG8_BAR; PG8_SCHED;
	s_add_i32 s33, 0, 0x18000
	s_add_i32 s36, 0, 0x1c000
	v_add_u32_e32 v158, s33, v174
	v_add_u32_e32 v185, s36, v174
	ds_read_b128 v[146:149], v158
	ds_read_b128 v[150:153], v158 offset:1024
	ds_read_b128 v[154:157], v158 offset:2048
	ds_read_b128 v[158:161], v158 offset:3072
	ds_read_b128 v[162:165], v185
	ds_read_b128 v[166:169], v185 offset:1024
	ds_read_b128 v[186:189], v185 offset:2048
	ds_read_b128 v[190:193], v185 offset:3072
	ds_read_b128 v[194:197], v177 offset:32768
	ds_read_b128 v[198:201], v177 offset:33792
	ds_read_b128 v[202:205], v177 offset:34816
	ds_read_b128 v[206:209], v177 offset:35840
	ds_read_b128 v[210:213], v177 offset:36864
	ds_read_b128 v[218:221], v177 offset:37888
	ds_read_b128 v[222:225], v177 offset:38912
	ds_read_b128 v[226:229], v177 offset:39936
	s_add_u32 s98, s60, 0x100000
	s_addc_u32 s99, s61, 0
	s_mov_b32 m0, s67
	s_nop 0
	global_load_lds_dwordx4 v136, s[98:99]
	s_mov_b32 m0, s68
	s_nop 0
	global_load_lds_dwordx4 v132, s[98:99]
	s_waitcnt vmcnt(8)
	s_waitcnt lgkmcnt(0)
	s_setprio 1
	s_waitcnt lgkmcnt(0)
	v_mfma_f32_16x16x32_bf16 v[126:129], v[146:149], v[194:197], v[126:129]
	v_mfma_f32_16x16x32_bf16 v[122:125], v[154:157], v[194:197], v[122:125]
	v_mfma_f32_16x16x32_bf16 v[118:121], v[146:149], v[202:205], v[118:121]
	v_mfma_f32_16x16x32_bf16 v[114:117], v[154:157], v[202:205], v[114:117]
	v_mfma_f32_16x16x32_bf16 v[110:113], v[146:149], v[210:213], v[110:113]
	v_mfma_f32_16x16x32_bf16 v[102:105], v[154:157], v[210:213], v[102:105]
	v_mfma_f32_16x16x32_bf16 v[94:97], v[146:149], v[222:225], v[94:97]
	v_mfma_f32_16x16x32_bf16 v[86:89], v[154:157], v[222:225], v[86:89]
	v_mfma_f32_16x16x32_bf16 v[126:129], v[150:153], v[198:201], v[126:129]
	v_mfma_f32_16x16x32_bf16 v[122:125], v[158:161], v[198:201], v[122:125]
	v_mfma_f32_16x16x32_bf16 v[118:121], v[150:153], v[206:209], v[118:121]
	v_mfma_f32_16x16x32_bf16 v[114:117], v[158:161], v[206:209], v[114:117]
	v_mfma_f32_16x16x32_bf16 v[110:113], v[150:153], v[218:221], v[110:113]
	v_mfma_f32_16x16x32_bf16 v[102:105], v[158:161], v[218:221], v[102:105]
	v_mfma_f32_16x16x32_bf16 v[94:97], v[150:153], v[226:229], v[94:97]
	v_mfma_f32_16x16x32_bf16 v[86:89], v[158:161], v[226:229], v[86:89]
	s_setprio 0
	s_setprio 1
	v_mfma_f32_16x16x32_bf16 v[106:109], v[162:165], v[194:197], v[106:109]
	v_mfma_f32_16x16x32_bf16 v[98:101], v[186:189], v[194:197], v[98:101]
	v_mfma_f32_16x16x32_bf16 v[90:93], v[162:165], v[202:205], v[90:93]
	v_mfma_f32_16x16x32_bf16 v[82:85], v[186:189], v[202:205], v[82:85]
	v_mfma_f32_16x16x32_bf16 v[78:81], v[162:165], v[210:213], v[78:81]
	v_mfma_f32_16x16x32_bf16 v[74:77], v[186:189], v[210:213], v[74:77]
	v_mfma_f32_16x16x32_bf16 v[70:73], v[162:165], v[222:225], v[70:73]
	v_mfma_f32_16x16x32_bf16 v[66:69], v[186:189], v[222:225], v[66:69]
	v_mfma_f32_16x16x32_bf16 v[106:109], v[166:169], v[198:201], v[106:109]
	v_mfma_f32_16x16x32_bf16 v[98:101], v[190:193], v[198:201], v[98:101]
	v_mfma_f32_16x16x32_bf16 v[90:93], v[166:169], v[206:209], v[90:93]
	v_mfma_f32_16x16x32_bf16 v[82:85], v[190:193], v[206:209], v[82:85]
	v_mfma_f32_16x16x32_bf16 v[78:81], v[166:169], v[218:221], v[78:81]
	v_mfma_f32_16x16x32_bf16 v[74:77], v[190:193], v[218:221], v[74:77]
	v_mfma_f32_16x16x32_bf16 v[70:73], v[166:169], v[226:229], v[70:73]
	v_mfma_f32_16x16x32_bf16 v[66:69], v[190:193], v[226:229], v[66:69]
	s_setprio 0
	s_barrier
	ds_read_b128 v[194:197], v177 offset:49152
	ds_read_b128 v[198:201], v177 offset:50176
	ds_read_b128 v[202:205], v177 offset:51200
	ds_read_b128 v[206:209], v177 offset:52224
	ds_read_b128 v[210:213], v177 offset:53248
	ds_read_b128 v[218:221], v177 offset:54272
	ds_read_b128 v[222:225], v177 offset:55296
	ds_read_b128 v[226:229], v177 offset:56320
	s_add_u32 s98, s58, 0x80
	s_addc_u32 s99, s59, 0
	s_add_u32 s100, s58, 0x80080
	s_addc_u32 s101, s59, 0
	s_add_u32 s24, s60, 0x80
	s_addc_u32 s25, s61, 0
	s_add_i32 m0, s62, 0x18000
	s_nop 0
	global_load_lds_dwordx4 v134, s[98:99]
	s_add_i32 m0, s62, 0x1a000
	s_nop 0
	global_load_lds_dwordx4 v130, s[98:99]
	s_add_i32 m0, s62, 0x1c000
	s_nop 0
	global_load_lds_dwordx4 v134, s[100:101]
	s_add_i32 m0, s62, 0x1e000
	s_nop 0
	global_load_lds_dwordx4 v130, s[100:101]
	s_mov_b32 m0, s71
	s_nop 0
	global_load_lds_dwordx4 v136, s[24:25]
	s_mov_b32 m0, s72
	s_nop 0
	global_load_lds_dwordx4 v132, s[24:25]
	s_waitcnt vmcnt(8)
	s_waitcnt lgkmcnt(0)
	s_setprio 1
	s_waitcnt lgkmcnt(0)
	v_mfma_f32_16x16x32_bf16 v[62:65], v[146:149], v[194:197], v[62:65]
	v_mfma_f32_16x16x32_bf16 v[58:61], v[154:157], v[194:197], v[58:61]
	v_mfma_f32_16x16x32_bf16 v[54:57], v[146:149], v[202:205], v[54:57]
	v_mfma_f32_16x16x32_bf16 v[50:53], v[154:157], v[202:205], v[50:53]
	v_mfma_f32_16x16x32_bf16 v[38:41], v[146:149], v[210:213], v[38:41]
	v_mfma_f32_16x16x32_bf16 v[34:37], v[154:157], v[210:213], v[34:37]
	v_mfma_f32_16x16x32_bf16 v[22:25], v[146:149], v[222:225], v[22:25]
	v_mfma_f32_16x16x32_bf16 v[18:21], v[154:157], v[222:225], v[18:21]
	v_mfma_f32_16x16x32_bf16 v[62:65], v[150:153], v[198:201], v[62:65]
	v_mfma_f32_16x16x32_bf16 v[58:61], v[158:161], v[198:201], v[58:61]
	v_mfma_f32_16x16x32_bf16 v[54:57], v[150:153], v[206:209], v[54:57]
	v_mfma_f32_16x16x32_bf16 v[50:53], v[158:161], v[206:209], v[50:53]
	v_mfma_f32_16x16x32_bf16 v[38:41], v[150:153], v[218:221], v[38:41]
	v_mfma_f32_16x16x32_bf16 v[34:37], v[158:161], v[218:221], v[34:37]
	v_mfma_f32_16x16x32_bf16 v[22:25], v[150:153], v[226:229], v[22:25]
	v_mfma_f32_16x16x32_bf16 v[18:21], v[158:161], v[226:229], v[18:21]
	s_setprio 0
	s_setprio 1
	v_mfma_f32_16x16x32_bf16 v[46:49], v[162:165], v[194:197], v[46:49]
	v_mfma_f32_16x16x32_bf16 v[42:45], v[186:189], v[194:197], v[42:45]
	v_mfma_f32_16x16x32_bf16 v[30:33], v[162:165], v[202:205], v[30:33]
	v_mfma_f32_16x16x32_bf16 v[26:29], v[186:189], v[202:205], v[26:29]
	v_mfma_f32_16x16x32_bf16 v[14:17], v[162:165], v[210:213], v[14:17]
	v_mfma_f32_16x16x32_bf16 v[10:13], v[186:189], v[210:213], v[10:13]
	v_mfma_f32_16x16x32_bf16 v[6:9], v[162:165], v[222:225], v[6:9]
	v_mfma_f32_16x16x32_bf16 v[2:5], v[186:189], v[222:225], v[2:5]
	v_mfma_f32_16x16x32_bf16 v[46:49], v[166:169], v[198:201], v[46:49]
	v_mfma_f32_16x16x32_bf16 v[42:45], v[190:193], v[198:201], v[42:45]
	v_mfma_f32_16x16x32_bf16 v[30:33], v[166:169], v[206:209], v[30:33]
	v_mfma_f32_16x16x32_bf16 v[26:29], v[190:193], v[206:209], v[26:29]
	v_mfma_f32_16x16x32_bf16 v[14:17], v[166:169], v[218:221], v[14:17]
	v_mfma_f32_16x16x32_bf16 v[10:13], v[190:193], v[218:221], v[10:13]
	v_mfma_f32_16x16x32_bf16 v[6:9], v[166:169], v[226:229], v[6:9]
	v_mfma_f32_16x16x32_bf16 v[2:5], v[190:193], v[226:229], v[2:5]
	s_setprio 0
	s_barrier
	s_add_i32 s29, s29, 2
	s_add_u32 s27, s27, 0x100
	s_addc_u32 s28, s28, 0
	s_cmp_gt_u32 s29, 29
	s_mov_b64 s[56:57], s[6:7]
	s_cbranch_scc0 .LBB0_917
	s_branch .Lk3_exit
; #define PG8_STAGE(bufoff, gbase, voff) do { _Pragma("unroll") for (int _i = 0; _i < 2; ++_i) \
;         __builtin_amdgcn_global_load_lds((const unsigned*)((const char*)(gbase) + (voff)[_i]), (PG8_LAS unsigned*)(lds + (bufoff) + ldsw + _i * 8192), 16, 0, 0); } while (0)
; #define PG8_LDA(dst, b, h) do { _Pragma("unroll") for (int m = 0; m < 4; ++m) _Pragma("unroll") for (int k = 0; k < 2; ++k) dst[m][k] = *(const PG8_LAS bf16x8*)(lds + PG8_SA(b, h) + aoff + m * 2048 + k * 1024); } while (0)
; #define PG8_LDB(dst, b, h) do { _Pragma("unroll") for (int n = 0; n < 2; ++n) _Pragma("unroll") for (int k = 0; k < 2; ++k) dst[n][k] = *(const PG8_LAS bf16x8*)(lds + PG8_SB(b, h) + boff + n * 2048 + k * 1024); } while (0)
; #define PG8_WAIT_V(n) asm volatile("s_waitcnt vmcnt(" #n ")" ::: "memory")
; #define PG8_WAIT_L(n) asm volatile("s_waitcnt lgkmcnt(" #n ")" ::: "memory")
; #define PG8_BAR __builtin_amdgcn_s_barrier()
; #define PG8_SCHED __builtin_amdgcn_sched_barrier(0)
; template <class Epi, class Sched, bool ALIGN_EPI = false, bool SP2 = false, bool F8 = false>
; __device__ __forceinline__ void gemm_phase(PG8_LAS unsigned char* lds, const Gemm g, const Sched& S, const Epi& E) {
;     ...
;             PG8_LDB(B0, 0, 0); PG8_LDB(B1, 0, 1); PG8_SCHED; PG8_LDA(At, 0, 0); PG8_STAGE(PG8_SA(1, 1), a1 + hstepA, voffA);
;             PG8_WAIT_V(8); PG8_WAIT_L(0); PG8_BAR; PG8_MMA(0, 0, At, B0); PG8_MMA(0, 1, At, B1); PG8_BAR; PG8_SCHED;
;             PG8_LDA(At, 0, 1); PG8_STAGE(PG8_SB(0, 0), b2, voffB); PG8_STAGE(PG8_SB(0, 1), b2 + hstep, voffB); PG8_STAGE(PG8_SA(0, 0), a2, voffA);
;             PG8_WAIT_V(8); PG8_WAIT_L(0); PG8_BAR; PG8_MMA(1, 0, At, B0); PG8_MMA(1, 1, At, B1); PG8_BAR; PG8_SCHED;
.Lk3_Y:
	ds_read_b128 v[146:149], v175
	ds_read_b128 v[150:153], v175 offset:1024
	ds_read_b128 v[154:157], v175 offset:2048
	ds_read_b128 v[158:161], v175 offset:3072
	ds_read_b128 v[162:165], v176
	ds_read_b128 v[166:169], v176 offset:1024
	ds_read_b128 v[186:189], v176 offset:2048
	ds_read_b128 v[190:193], v176 offset:3072
	s_add_u32 s6, s56, 0x100
	s_addc_u32 s7, s57, 0
	s_cmp_eq_u32 s29, 28
	s_cselect_b32 s61, s53, s7
	s_cselect_b32 s60, s52, s6
	s_cselect_b32 s59, s15, s28
	s_cselect_b32 s58, s26, s27
	ds_read_b128 v[194:197], v177
	ds_read_b128 v[198:201], v177 offset:1024
	ds_read_b128 v[202:205], v177 offset:2048
	ds_read_b128 v[206:209], v177 offset:3072
	ds_read_b128 v[210:213], v177 offset:4096
	ds_read_b128 v[218:221], v177 offset:5120
	ds_read_b128 v[222:225], v177 offset:6144
	ds_read_b128 v[226:229], v177 offset:7168
	s_add_i32 m0, s65, 0xc000
	s_nop 0
	global_load_lds_dwordx4 v138, s[56:57]
	s_add_i32 m0, s65, 0xe000
	s_nop 0
	global_load_lds_dwordx4 v140, s[56:57]
	s_waitcnt vmcnt(8)
	s_waitcnt lgkmcnt(0)
	s_barrier
	s_setprio 3
	s_waitcnt lgkmcnt(0)
	v_mfma_f32_16x16x32_bf16 v[126:129], v[146:149], v[194:197], v[126:129]
	v_mfma_f32_16x16x32_bf16 v[122:125], v[154:157], v[194:197], v[122:125]
	v_mfma_f32_16x16x32_bf16 v[118:121], v[146:149], v[202:205], v[118:121]
	v_mfma_f32_16x16x32_bf16 v[114:117], v[154:157], v[202:205], v[114:117]
	v_mfma_f32_16x16x32_bf16 v[110:113], v[146:149], v[210:213], v[110:113]
	v_mfma_f32_16x16x32_bf16 v[102:105], v[154:157], v[210:213], v[102:105]
	v_mfma_f32_16x16x32_bf16 v[94:97], v[146:149], v[222:225], v[94:97]
	v_mfma_f32_16x16x32_bf16 v[86:89], v[154:157], v[222:225], v[86:89]
	v_mfma_f32_16x16x32_bf16 v[126:129], v[150:153], v[198:201], v[126:129]
	v_mfma_f32_16x16x32_bf16 v[122:125], v[158:161], v[198:201], v[122:125]
	v_mfma_f32_16x16x32_bf16 v[118:121], v[150:153], v[206:209], v[118:121]
	v_mfma_f32_16x16x32_bf16 v[114:117], v[158:161], v[206:209], v[114:117]
	v_mfma_f32_16x16x32_bf16 v[110:113], v[150:153], v[218:221], v[110:113]
	v_mfma_f32_16x16x32_bf16 v[102:105], v[158:161], v[218:221], v[102:105]
	v_mfma_f32_16x16x32_bf16 v[94:97], v[150:153], v[226:229], v[94:97]
	v_mfma_f32_16x16x32_bf16 v[86:89], v[158:161], v[226:229], v[86:89]
	s_setprio 0
	s_setprio 3
	v_mfma_f32_16x16x32_bf16 v[106:109], v[162:165], v[194:197], v[106:109]
	v_mfma_f32_16x16x32_bf16 v[98:101], v[186:189], v[194:197], v[98:101]
	v_mfma_f32_16x16x32_bf16 v[90:93], v[162:165], v[202:205], v[90:93]
	v_mfma_f32_16x16x32_bf16 v[82:85], v[186:189], v[202:205], v[82:85]
	v_mfma_f32_16x16x32_bf16 v[78:81], v[162:165], v[210:213], v[78:81]
	v_mfma_f32_16x16x32_bf16 v[74:77], v[186:189], v[210:213], v[74:77]
	v_mfma_f32_16x16x32_bf16 v[70:73], v[162:165], v[222:225], v[70:73]
	v_mfma_f32_16x16x32_bf16 v[66:69], v[186:189], v[222:225], v[66:69]
	v_mfma_f32_16x16x32_bf16 v[106:109], v[166:169], v[198:201], v[106:109]
	v_mfma_f32_16x16x32_bf16 v[98:101], v[190:193], v[198:201], v[98:101]
	v_mfma_f32_16x16x32_bf16 v[90:93], v[166:169], v[206:209], v[90:93]
	v_mfma_f32_16x16x32_bf16 v[82:85], v[190:193], v[206:209], v[82:85]
	v_mfma_f32_16x16x32_bf16 v[78:81], v[166:169], v[218:221], v[78:81]
	v_mfma_f32_16x16x32_bf16 v[74:77], v[190:193], v[218:221], v[74:77]
	v_mfma_f32_16x16x32_bf16 v[70:73], v[166:169], v[226:229], v[70:73]
	v_mfma_f32_16x16x32_bf16 v[66:69], v[190:193], v[226:229], v[66:69]
	s_setprio 0
	ds_read_b128 v[194:197], v177 offset:16384
	ds_read_b128 v[198:201], v177 offset:17408
	ds_read_b128 v[202:205], v177 offset:18432
	ds_read_b128 v[206:209], v177 offset:19456
	ds_read_b128 v[210:213], v177 offset:20480
	ds_read_b128 v[218:221], v177 offset:21504
	ds_read_b128 v[222:225], v177 offset:22528
	ds_read_b128 v[226:229], v177 offset:23552
	s_add_u32 s98, s58, 0x80000
	s_addc_u32 s99, s59, 0
	s_add_i32 s100, s75, s62
	s_add_i32 s101, s76, s62
	s_mov_b32 m0, s100
	s_nop 0
	global_load_lds_dwordx4 v134, s[58:59]
	s_add_i32 m0, s100, 0x2000
	s_nop 0
	global_load_lds_dwordx4 v130, s[58:59]
	s_mov_b32 m0, s101
	s_nop 0
	global_load_lds_dwordx4 v134, s[98:99]
	s_add_i32 m0, s101, 0x2000
	s_nop 0
	global_load_lds_dwordx4 v130, s[98:99]
	s_mov_b32 m0, s65
	s_nop 0
	global_load_lds_dwordx4 v136, s[60:61]
	s_mov_b32 m0, s66
	s_nop 0
	global_load_lds_dwordx4 v132, s[60:61]
	s_waitcnt vmcnt(8)
	s_waitcnt lgkmcnt(0)
	s_barrier
; #define PG8_STAGE(bufoff, gbase, voff) do { _Pragma("unroll") for (int _i = 0; _i < 2; ++_i) \
;         __builtin_amdgcn_global_load_lds((const unsigned*)((const char*)(gbase) + (voff)[_i]), (PG8_LAS unsigned*)(lds + (bufoff) + ldsw + _i * 8192), 16, 0, 0); } while (0)
; #define PG8_LDA(dst, b, h) do { _Pragma("unroll") for (int m = 0; m < 4; ++m) _Pragma("unroll") for (int k = 0; k < 2; ++k) dst[m][k] = *(const PG8_LAS bf16x8*)(lds + PG8_SA(b, h) + aoff + m * 2048 + k * 1024); } while (0)
; #define PG8_LDB(dst, b, h) do { _Pragma("unroll") for (int n = 0; n < 2; ++n) _Pragma("unroll") for (int k = 0; k < 2; ++k) dst[n][k] = *(const PG8_LAS bf16x8*)(lds + PG8_SB(b, h) + boff + n * 2048 + k * 1024); } while (0)
; #define PG8_WAIT_V(n) asm volatile("s_waitcnt vmcnt(" #n ")" ::: "memory")
; #define PG8_WAIT_L(n) asm volatile("s_waitcnt lgkmcnt(" #n ")" ::: "memory")
; #define PG8_BAR __builtin_amdgcn_s_barrier()
; #define PG8_SCHED __builtin_amdgcn_sched_barrier(0)
; template <class Epi, class Sched, bool ALIGN_EPI = false, bool SP2 = false, bool F8 = false>
; __device__ __forceinline__ void gemm_phase(PG8_LAS unsigned char* lds, const Gemm g, const Sched& S, const Epi& E) {
;     ...
;             PG8_WAIT_V(8); PG8_WAIT_L(0); PG8_BAR; PG8_MMA(1, 0, At, B0); PG8_MMA(1, 1, At, B1); PG8_BAR; PG8_SCHED;
;             PG8_LDB(B0, 1, 0); PG8_LDB(B1, 1, 1); PG8_SCHED; PG8_LDA(At, 1, 0); PG8_STAGE(PG8_SA(0, 1), a2 + hstepA, voffA);
;             PG8_WAIT_V(8); PG8_WAIT_L(0); PG8_BAR; PG8_MMA(0, 0, At, B0); PG8_MMA(0, 1, At, B1); PG8_BAR; PG8_SCHED;
;             PG8_LDA(At, 1, 1); PG8_STAGE(PG8_SB(1, 0), b3, voffB); PG8_STAGE(PG8_SB(1, 1), b3 + hstep, voffB); PG8_STAGE(PG8_SA(1, 0), a3, voffA);
	s_setprio 3
	s_waitcnt lgkmcnt(0)
	v_mfma_f32_16x16x32_bf16 v[62:65], v[146:149], v[194:197], v[62:65]
	v_mfma_f32_16x16x32_bf16 v[58:61], v[154:157], v[194:197], v[58:61]
	v_mfma_f32_16x16x32_bf16 v[54:57], v[146:149], v[202:205], v[54:57]
	v_mfma_f32_16x16x32_bf16 v[50:53], v[154:157], v[202:205], v[50:53]
	v_mfma_f32_16x16x32_bf16 v[38:41], v[146:149], v[210:213], v[38:41]
	v_mfma_f32_16x16x32_bf16 v[34:37], v[154:157], v[210:213], v[34:37]
	v_mfma_f32_16x16x32_bf16 v[22:25], v[146:149], v[222:225], v[22:25]
	v_mfma_f32_16x16x32_bf16 v[18:21], v[154:157], v[222:225], v[18:21]
	v_mfma_f32_16x16x32_bf16 v[62:65], v[150:153], v[198:201], v[62:65]
	v_mfma_f32_16x16x32_bf16 v[58:61], v[158:161], v[198:201], v[58:61]
	v_mfma_f32_16x16x32_bf16 v[54:57], v[150:153], v[206:209], v[54:57]
	v_mfma_f32_16x16x32_bf16 v[50:53], v[158:161], v[206:209], v[50:53]
	v_mfma_f32_16x16x32_bf16 v[38:41], v[150:153], v[218:221], v[38:41]
	v_mfma_f32_16x16x32_bf16 v[34:37], v[158:161], v[218:221], v[34:37]
	v_mfma_f32_16x16x32_bf16 v[22:25], v[150:153], v[226:229], v[22:25]
	v_mfma_f32_16x16x32_bf16 v[18:21], v[158:161], v[226:229], v[18:21]
	s_setprio 0
	s_setprio 3
	v_mfma_f32_16x16x32_bf16 v[46:49], v[162:165], v[194:197], v[46:49]
	v_mfma_f32_16x16x32_bf16 v[42:45], v[186:189], v[194:197], v[42:45]
	v_mfma_f32_16x16x32_bf16 v[30:33], v[162:165], v[202:205], v[30:33]
	v_mfma_f32_16x16x32_bf16 v[26:29], v[186:189], v[202:205], v[26:29]
	v_mfma_f32_16x16x32_bf16 v[14:17], v[162:165], v[210:213], v[14:17]
	v_mfma_f32_16x16x32_bf16 v[10:13], v[186:189], v[210:213], v[10:13]
	v_mfma_f32_16x16x32_bf16 v[6:9], v[162:165], v[222:225], v[6:9]
	v_mfma_f32_16x16x32_bf16 v[2:5], v[186:189], v[222:225], v[2:5]
	v_mfma_f32_16x16x32_bf16 v[46:49], v[166:169], v[198:201], v[46:49]
	v_mfma_f32_16x16x32_bf16 v[42:45], v[190:193], v[198:201], v[42:45]
	v_mfma_f32_16x16x32_bf16 v[30:33], v[166:169], v[206:209], v[30:33]
	v_mfma_f32_16x16x32_bf16 v[26:29], v[190:193], v[206:209], v[26:29]
	v_mfma_f32_16x16x32_bf16 v[14:17], v[166:169], v[218:221], v[14:17]
	v_mfma_f32_16x16x32_bf16 v[10:13], v[190:193], v[218:221], v[10:13]
	v_mfma_f32_16x16x32_bf16 v[6:9], v[166:169], v[226:229], v[6:9]
	v_mfma_f32_16x16x32_bf16 v[2:5], v[190:193], v[226:229], v[2:5]
	s_setprio 0
	s_add_i32 s33, 0, 0x18000
	s_add_i32 s36, 0, 0x1c000
	v_add_u32_e32 v158, s33, v174
	v_add_u32_e32 v185, s36, v174
	ds_read_b128 v[146:149], v158
	ds_read_b128 v[150:153], v158 offset:1024
	ds_read_b128 v[154:157], v158 offset:2048
	ds_read_b128 v[158:161], v158 offset:3072
	ds_read_b128 v[162:165], v185
	ds_read_b128 v[166:169], v185 offset:1024
	ds_read_b128 v[186:189], v185 offset:2048
	ds_read_b128 v[190:193], v185 offset:3072
	ds_read_b128 v[194:197], v177 offset:32768
	ds_read_b128 v[198:201], v177 offset:33792
	ds_read_b128 v[202:205], v177 offset:34816
	ds_read_b128 v[206:209], v177 offset:35840
	ds_read_b128 v[210:213], v177 offset:36864
	ds_read_b128 v[218:221], v177 offset:37888
	ds_read_b128 v[222:225], v177 offset:38912
	ds_read_b128 v[226:229], v177 offset:39936
	s_add_u32 s98, s60, 0x100000
	s_addc_u32 s99, s61, 0
	s_mov_b32 m0, s67
	s_nop 0
	global_load_lds_dwordx4 v136, s[98:99]
	s_mov_b32 m0, s68
	s_nop 0
	global_load_lds_dwordx4 v132, s[98:99]
	s_waitcnt vmcnt(8)
	s_waitcnt lgkmcnt(0)
	s_barrier
; #define PG8_STAGE(bufoff, gbase, voff) do { _Pragma("unroll") for (int _i = 0; _i < 2; ++_i) \
;         __builtin_amdgcn_global_load_lds((const unsigned*)((const char*)(gbase) + (voff)[_i]), (PG8_LAS unsigned*)(lds + (bufoff) + ldsw + _i * 8192), 16, 0, 0); } while (0)
; #define PG8_LDA(dst, b, h) do { _Pragma("unroll") for (int m = 0; m < 4; ++m) _Pragma("unroll") for (int k = 0; k < 2; ++k) dst[m][k] = *(const PG8_LAS bf16x8*)(lds + PG8_SA(b, h) + aoff + m * 2048 + k * 1024); } while (0)
; #define PG8_WAIT_V(n) asm volatile("s_waitcnt vmcnt(" #n ")" ::: "memory")
; #define PG8_WAIT_L(n) asm volatile("s_waitcnt lgkmcnt(" #n ")" ::: "memory")
; #define PG8_BAR __builtin_amdgcn_s_barrier()
; #define PG8_SCHED __builtin_amdgcn_sched_barrier(0)
; template <class Epi, class Sched, bool ALIGN_EPI = false, bool SP2 = false, bool F8 = false>
; __device__ __forceinline__ void gemm_phase(PG8_LAS unsigned char* lds, const Gemm g, const Sched& S, const Epi& E) {
;     ...
;         for (int t = 0; t < nt; t += 2) {
;     ...
;             PG8_WAIT_V(8); PG8_WAIT_L(0); PG8_BAR; PG8_MMA(0, 0, At, B0); PG8_MMA(0, 1, At, B1); PG8_BAR; PG8_SCHED;
;             PG8_LDA(At, 1, 1); PG8_STAGE(PG8_SB(1, 0), b3, voffB); PG8_STAGE(PG8_SB(1, 1), b3 + hstep, voffB); PG8_STAGE(PG8_SA(1, 0), a3, voffA);
;             PG8_WAIT_V(8); PG8_WAIT_L(0); PG8_BAR; PG8_MMA(1, 0, At, B0); PG8_MMA(1, 1, At, B1); PG8_BAR; PG8_SCHED;
	s_setprio 3
	s_waitcnt lgkmcnt(0)
	v_mfma_f32_16x16x32_bf16 v[126:129], v[146:149], v[194:197], v[126:129]
	v_mfma_f32_16x16x32_bf16 v[122:125], v[154:157], v[194:197], v[122:125]
	v_mfma_f32_16x16x32_bf16 v[118:121], v[146:149], v[202:205], v[118:121]
	v_mfma_f32_16x16x32_bf16 v[114:117], v[154:157], v[202:205], v[114:117]
	v_mfma_f32_16x16x32_bf16 v[110:113], v[146:149], v[210:213], v[110:113]
	v_mfma_f32_16x16x32_bf16 v[102:105], v[154:157], v[210:213], v[102:105]
	v_mfma_f32_16x16x32_bf16 v[94:97], v[146:149], v[222:225], v[94:97]
	v_mfma_f32_16x16x32_bf16 v[86:89], v[154:157], v[222:225], v[86:89]
	v_mfma_f32_16x16x32_bf16 v[126:129], v[150:153], v[198:201], v[126:129]
	v_mfma_f32_16x16x32_bf16 v[122:125], v[158:161], v[198:201], v[122:125]
	v_mfma_f32_16x16x32_bf16 v[118:121], v[150:153], v[206:209], v[118:121]
	v_mfma_f32_16x16x32_bf16 v[114:117], v[158:161], v[206:209], v[114:117]
	v_mfma_f32_16x16x32_bf16 v[110:113], v[150:153], v[218:221], v[110:113]
	v_mfma_f32_16x16x32_bf16 v[102:105], v[158:161], v[218:221], v[102:105]
	v_mfma_f32_16x16x32_bf16 v[94:97], v[150:153], v[226:229], v[94:97]
	v_mfma_f32_16x16x32_bf16 v[86:89], v[158:161], v[226:229], v[86:89]
	s_setprio 0
	s_setprio 3
	v_mfma_f32_16x16x32_bf16 v[106:109], v[162:165], v[194:197], v[106:109]
	v_mfma_f32_16x16x32_bf16 v[98:101], v[186:189], v[194:197], v[98:101]
	v_mfma_f32_16x16x32_bf16 v[90:93], v[162:165], v[202:205], v[90:93]
	v_mfma_f32_16x16x32_bf16 v[82:85], v[186:189], v[202:205], v[82:85]
	v_mfma_f32_16x16x32_bf16 v[78:81], v[162:165], v[210:213], v[78:81]
	v_mfma_f32_16x16x32_bf16 v[74:77], v[186:189], v[210:213], v[74:77]
	v_mfma_f32_16x16x32_bf16 v[70:73], v[162:165], v[222:225], v[70:73]
	v_mfma_f32_16x16x32_bf16 v[66:69], v[186:189], v[222:225], v[66:69]
	v_mfma_f32_16x16x32_bf16 v[106:109], v[166:169], v[198:201], v[106:109]
	v_mfma_f32_16x16x32_bf16 v[98:101], v[190:193], v[198:201], v[98:101]
	v_mfma_f32_16x16x32_bf16 v[90:93], v[166:169], v[206:209], v[90:93]
	v_mfma_f32_16x16x32_bf16 v[82:85], v[190:193], v[206:209], v[82:85]
	v_mfma_f32_16x16x32_bf16 v[78:81], v[166:169], v[218:221], v[78:81]
	v_mfma_f32_16x16x32_bf16 v[74:77], v[190:193], v[218:221], v[74:77]
	v_mfma_f32_16x16x32_bf16 v[70:73], v[166:169], v[226:229], v[70:73]
	v_mfma_f32_16x16x32_bf16 v[66:69], v[190:193], v[226:229], v[66:69]
	s_setprio 0
	ds_read_b128 v[194:197], v177 offset:49152
	ds_read_b128 v[198:201], v177 offset:50176
	ds_read_b128 v[202:205], v177 offset:51200
	ds_read_b128 v[206:209], v177 offset:52224
	ds_read_b128 v[210:213], v177 offset:53248
	ds_read_b128 v[218:221], v177 offset:54272
	ds_read_b128 v[222:225], v177 offset:55296
	ds_read_b128 v[226:229], v177 offset:56320
	s_add_u32 s98, s58, 0x80
	s_addc_u32 s99, s59, 0
	s_add_u32 s100, s58, 0x80080
	s_addc_u32 s101, s59, 0
	s_add_u32 s24, s60, 0x80
	s_addc_u32 s25, s61, 0
	s_add_i32 m0, s62, 0x18000
	s_nop 0
	global_load_lds_dwordx4 v134, s[98:99]
	s_add_i32 m0, s62, 0x1a000
	s_nop 0
	global_load_lds_dwordx4 v130, s[98:99]
	s_add_i32 m0, s62, 0x1c000
	s_nop 0
	global_load_lds_dwordx4 v134, s[100:101]
	s_add_i32 m0, s62, 0x1e000
	s_nop 0
	global_load_lds_dwordx4 v130, s[100:101]
	s_mov_b32 m0, s71
	s_nop 0
	global_load_lds_dwordx4 v136, s[24:25]
	s_mov_b32 m0, s72
	s_nop 0
	global_load_lds_dwordx4 v132, s[24:25]
	s_waitcnt vmcnt(8)
	s_waitcnt lgkmcnt(0)
	s_barrier
	s_setprio 3
	s_waitcnt lgkmcnt(0)
	v_mfma_f32_16x16x32_bf16 v[62:65], v[146:149], v[194:197], v[62:65]
	v_mfma_f32_16x16x32_bf16 v[58:61], v[154:157], v[194:197], v[58:61]
	v_mfma_f32_16x16x32_bf16 v[54:57], v[146:149], v[202:205], v[54:57]
	v_mfma_f32_16x16x32_bf16 v[50:53], v[154:157], v[202:205], v[50:53]
	v_mfma_f32_16x16x32_bf16 v[38:41], v[146:149], v[210:213], v[38:41]
	v_mfma_f32_16x16x32_bf16 v[34:37], v[154:157], v[210:213], v[34:37]
	v_mfma_f32_16x16x32_bf16 v[22:25], v[146:149], v[222:225], v[22:25]
	v_mfma_f32_16x16x32_bf16 v[18:21], v[154:157], v[222:225], v[18:21]
	v_mfma_f32_16x16x32_bf16 v[62:65], v[150:153], v[198:201], v[62:65]
	v_mfma_f32_16x16x32_bf16 v[58:61], v[158:161], v[198:201], v[58:61]
	v_mfma_f32_16x16x32_bf16 v[54:57], v[150:153], v[206:209], v[54:57]
	v_mfma_f32_16x16x32_bf16 v[50:53], v[158:161], v[206:209], v[50:53]
	v_mfma_f32_16x16x32_bf16 v[38:41], v[150:153], v[218:221], v[38:41]
	v_mfma_f32_16x16x32_bf16 v[34:37], v[158:161], v[218:221], v[34:37]
	v_mfma_f32_16x16x32_bf16 v[22:25], v[150:153], v[226:229], v[22:25]
	v_mfma_f32_16x16x32_bf16 v[18:21], v[158:161], v[226:229], v[18:21]
	s_setprio 0
	s_setprio 3
	v_mfma_f32_16x16x32_bf16 v[46:49], v[162:165], v[194:197], v[46:49]
	v_mfma_f32_16x16x32_bf16 v[42:45], v[186:189], v[194:197], v[42:45]
	v_mfma_f32_16x16x32_bf16 v[30:33], v[162:165], v[202:205], v[30:33]
	v_mfma_f32_16x16x32_bf16 v[26:29], v[186:189], v[202:205], v[26:29]
	v_mfma_f32_16x16x32_bf16 v[14:17], v[162:165], v[210:213], v[14:17]
	v_mfma_f32_16x16x32_bf16 v[10:13], v[186:189], v[210:213], v[10:13]
	v_mfma_f32_16x16x32_bf16 v[6:9], v[162:165], v[222:225], v[6:9]
	v_mfma_f32_16x16x32_bf16 v[2:5], v[186:189], v[222:225], v[2:5]
	v_mfma_f32_16x16x32_bf16 v[46:49], v[166:169], v[198:201], v[46:49]
	v_mfma_f32_16x16x32_bf16 v[42:45], v[190:193], v[198:201], v[42:45]
	v_mfma_f32_16x16x32_bf16 v[30:33], v[166:169], v[206:209], v[30:33]
	v_mfma_f32_16x16x32_bf16 v[26:29], v[190:193], v[206:209], v[26:29]
	v_mfma_f32_16x16x32_bf16 v[14:17], v[166:169], v[218:221], v[14:17]
	v_mfma_f32_16x16x32_bf16 v[10:13], v[190:193], v[218:221], v[10:13]
	v_mfma_f32_16x16x32_bf16 v[6:9], v[166:169], v[226:229], v[6:9]
	v_mfma_f32_16x16x32_bf16 v[2:5], v[190:193], v[226:229], v[2:5]
	s_setprio 0
	s_add_i32 s29, s29, 2
	s_add_u32 s27, s27, 0x100
	s_addc_u32 s28, s28, 0
	s_cmp_gt_u32 s29, 29
	s_mov_b64 s[56:57], s[6:7]
	s_cbranch_scc0 .Lk3_Y

; __global__ void __launch_bounds__(NTHR, 2) fwd_kernel(Args args) {
	.amdhsa_kernel _Z10fwd_kernel4Args
		.amdhsa_group_segment_fixed_size 0
		.amdhsa_private_segment_fixed_size 0
		.amdhsa_kernarg_size 424
		.amdhsa_user_sgpr_count 2
		.amdhsa_user_sgpr_dispatch_ptr 0
		.amdhsa_user_sgpr_queue_ptr 0
		.amdhsa_user_sgpr_kernarg_segment_ptr 1
		.amdhsa_user_sgpr_dispatch_id 0
		.amdhsa_user_sgpr_kernarg_preload_length 0
		.amdhsa_user_sgpr_kernarg_preload_offset 0
		.amdhsa_user_sgpr_private_segment_size 0
		.amdhsa_uses_dynamic_stack 0
		.amdhsa_enable_private_segment 0
		.amdhsa_system_sgpr_workgroup_id_x 1
		.amdhsa_system_sgpr_workgroup_id_y 0
		.amdhsa_system_sgpr_workgroup_id_z 0
		.amdhsa_system_sgpr_workgroup_info 0
		.amdhsa_system_vgpr_workitem_id 0
		.amdhsa_next_free_vgpr 256
		.amdhsa_next_free_sgpr 102
		.amdhsa_accum_offset 256
		.amdhsa_reserve_vcc 1
		.amdhsa_float_round_mode_32 0
		.amdhsa_float_round_mode_16_64 0
		.amdhsa_float_denorm_mode_32 3
		.amdhsa_float_denorm_mode_16_64 3
		.amdhsa_dx10_clamp 1
		.amdhsa_ieee_mode 1
		.amdhsa_fp16_overflow 0
		.amdhsa_tg_split 0
		.amdhsa_exception_fp_ieee_invalid_op 0
		.amdhsa_exception_fp_denorm_src 0
		.amdhsa_exception_fp_ieee_div_zero 0
		.amdhsa_exception_fp_ieee_overflow 0
		.amdhsa_exception_fp_ieee_underflow 0
		.amdhsa_exception_fp_ieee_inexact 0
		.amdhsa_exception_int_div_zero 0
	.end_amdhsa_kernel

; __global__ void __launch_bounds__(NTHR, 2) fwd_kernel(Args args) {
amdhsa.kernels:
  - .agpr_count:     0
    .args:
      - .offset:         0
        .size:           168
        .value_kind:     by_value
      - .offset:         168
        .size:           4
        .value_kind:     hidden_block_count_x
      - .offset:         172
        .size:           4
        .value_kind:     hidden_block_count_y
      - .offset:         176
        .size:           4
        .value_kind:     hidden_block_count_z
      - .offset:         180
        .size:           2
        .value_kind:     hidden_group_size_x
      - .offset:         182
        .size:           2
        .value_kind:     hidden_group_size_y
      - .offset:         184
        .size:           2
        .value_kind:     hidden_group_size_z
      - .offset:         186
        .size:           2
        .value_kind:     hidden_remainder_x
      - .offset:         188
        .size:           2
        .value_kind:     hidden_remainder_y
      - .offset:         190
        .size:           2
        .value_kind:     hidden_remainder_z
      - .offset:         208
        .size:           8
        .value_kind:     hidden_global_offset_x
      - .offset:         216
        .size:           8
        .value_kind:     hidden_global_offset_y
      - .offset:         224
        .size:           8
        .value_kind:     hidden_global_offset_z
      - .offset:         232
        .size:           2
        .value_kind:     hidden_grid_dims
      - .offset:         288
        .size:           4
        .value_kind:     hidden_dynamic_lds_size
    .group_segment_fixed_size: 0
    .kernarg_segment_align: 8
    .kernarg_segment_size: 424
    .language:       OpenCL C
    .language_version:
      - 2
      - 0
    .max_flat_workgroup_size: 512
    .name:           _Z10fwd_kernel4Args
    .private_segment_fixed_size: 0
    .sgpr_count:     108
    .sgpr_spill_count: 17
    .symbol:         _Z10fwd_kernel4Args.kd
    .uniform_work_group_size: 1
    .uses_dynamic_stack: false
    .vgpr_count:     256
    .vgpr_spill_count: 0
    .wavefront_size: 64
